# stick-breaking: partner-sum select folded into one fma per group; sparse attention mask init without the word inversion
# speedup vs baseline: 1.0009x; 1.0009x over previous
.LBB0_41:
	s_add_i32 s0, s42, -1
	v_cmp_le_i32_e32 vcc, s2, v198
	s_and_b32 s45, s0, 1
	s_cbranch_vccnz .LBB0_44
	v_cmp_gt_f32_e32 vcc, s58, v172
	s_cmp_eq_u64 vcc, exec
	s_cbranch_scc1 .LBB0_44
	s_mul_i32 s0, s45, 0x8c00
	s_add_i32 s0, s0, 0
	v_add_u32_e32 v0, s0, v189
	v_add_u32_e32 v173, v0, v188
	ds_read_b128 v[66:69], v173
	ds_read_b128 v[174:177], v173 offset:32
	ds_read_b128 v[82:85], v173 offset:8704
	ds_read_b128 v[200:203], v173 offset:8736
	ds_read_b128 v[204:207], v173 offset:64
	ds_read_b128 v[208:211], v173 offset:96
	ds_read_b128 v[212:215], v173 offset:8768
	ds_read_b128 v[216:219], v173 offset:8800
	s_setprio 1
	s_waitcnt lgkmcnt(7)
	v_mfma_f32_32x32x16_bf16 v[66:81], v[66:69], v[98:101], 0
	s_waitcnt lgkmcnt(5)
	v_mfma_f32_32x32x16_bf16 v[82:97], v[82:85], v[98:101], 0
	v_mfma_f32_32x32x16_bf16 v[66:81], v[174:177], v[102:105], v[66:81]
	s_waitcnt lgkmcnt(4)
	v_mfma_f32_32x32x16_bf16 v[82:97], v[200:203], v[102:105], v[82:97]
	s_waitcnt lgkmcnt(3)
	v_mfma_f32_32x32x16_bf16 v[66:81], v[204:207], v[106:109], v[66:81]
	s_waitcnt lgkmcnt(1)
	v_mfma_f32_32x32x16_bf16 v[82:97], v[212:215], v[106:109], v[82:97]
	v_mfma_f32_32x32x16_bf16 v[66:81], v[208:211], v[110:113], v[66:81]
	s_waitcnt lgkmcnt(0)
	v_mfma_f32_32x32x16_bf16 v[82:97], v[216:219], v[110:113], v[82:97]
	s_setprio 0
	ds_read_b128 v[174:177], v173 offset:128
	ds_read_b128 v[200:203], v173 offset:160
	ds_read_b128 v[204:207], v173 offset:8832
	ds_read_b128 v[208:211], v173 offset:8864
	ds_read_b128 v[212:215], v173 offset:192
	ds_read_b128 v[216:219], v173 offset:224
	ds_read_b128 v[220:223], v173 offset:8896
	ds_read_b128 v[224:227], v173 offset:8928
	s_setprio 1
	s_waitcnt lgkmcnt(7)
	v_mfma_f32_32x32x16_bf16 v[66:81], v[174:177], v[114:117], v[66:81]
	s_waitcnt lgkmcnt(5)
	v_mfma_f32_32x32x16_bf16 v[82:97], v[204:207], v[114:117], v[82:97]
	v_mfma_f32_32x32x16_bf16 v[66:81], v[200:203], v[118:121], v[66:81]
	s_waitcnt lgkmcnt(4)
	v_mfma_f32_32x32x16_bf16 v[82:97], v[208:211], v[118:121], v[82:97]
	s_waitcnt lgkmcnt(3)
	v_mfma_f32_32x32x16_bf16 v[66:81], v[212:215], v[122:125], v[66:81]
	s_waitcnt lgkmcnt(1)
	v_mfma_f32_32x32x16_bf16 v[82:97], v[220:223], v[122:125], v[82:97]
	v_mfma_f32_32x32x16_bf16 v[66:81], v[216:219], v[126:129], v[66:81]
	s_waitcnt lgkmcnt(0)
	v_mfma_f32_32x32x16_bf16 v[82:97], v[224:227], v[126:129], v[82:97]
	s_setprio 0
	s_nop 10
	v_mov_b32_e32 v236, 1.0
	v_cndmask_b32_e64 v173, 0, 1.0, s[4:5]
	v_cmp_gt_i32_e32 vcc, 28, v159
	s_cmp_eq_u64 vcc, 0
	s_cbranch_scc1 .Lstk_nm1
	v_cmp_lt_i32_e64 s[0:1], 0, v159
	v_cmp_lt_i32_e64 s[8:9], 1, v159
	v_cmp_lt_i32_e64 s[10:11], 2, v159
	v_cmp_lt_i32_e64 s[12:13], 3, v159
	v_cndmask_b32_e64 v82, v231, v82, s[0:1]
	v_cndmask_b32_e64 v83, v231, v83, s[8:9]
	v_cndmask_b32_e64 v84, v231, v84, s[10:11]
	v_cndmask_b32_e64 v85, v231, v85, s[12:13]
	v_cmp_lt_i32_e64 s[0:1], 8, v159
	v_cmp_lt_i32_e64 s[8:9], 9, v159
	v_cmp_lt_i32_e64 s[10:11], 10, v159
	v_cmp_lt_i32_e64 s[12:13], 11, v159
	v_cndmask_b32_e64 v86, v231, v86, s[0:1]
	v_cndmask_b32_e64 v87, v231, v87, s[8:9]
	v_cndmask_b32_e64 v88, v231, v88, s[10:11]
	v_cndmask_b32_e64 v89, v231, v89, s[12:13]
	v_cmp_lt_i32_e64 s[0:1], 16, v159
	v_cmp_lt_i32_e64 s[8:9], 17, v159
	v_cmp_lt_i32_e64 s[10:11], 18, v159
	v_cmp_lt_i32_e64 s[12:13], 19, v159
	v_cndmask_b32_e64 v90, v231, v90, s[0:1]
	v_cndmask_b32_e64 v91, v231, v91, s[8:9]
	v_cndmask_b32_e64 v92, v231, v92, s[10:11]
	v_cndmask_b32_e64 v93, v231, v93, s[12:13]
	v_cmp_lt_i32_e64 s[0:1], 24, v159
	v_cmp_lt_i32_e64 s[8:9], 25, v159
	v_cmp_lt_i32_e64 s[10:11], 26, v159
	v_cmp_lt_i32_e64 s[12:13], 27, v159
	v_cndmask_b32_e64 v94, v231, v94, s[0:1]
	v_cndmask_b32_e64 v95, v231, v95, s[8:9]
	v_cndmask_b32_e64 v96, v231, v96, s[10:11]
	v_cndmask_b32_e64 v97, v231, v97, s[12:13]
.Lstk_nm1:
	v_exp_f32_e64 v200, -|v82|
	v_exp_f32_e64 v201, -|v83|
	v_exp_f32_e64 v202, -|v84|
	v_exp_f32_e64 v203, -|v85|
	v_pk_add_f32 v[200:201], v[200:201], v[236:237] op_sel_hi:[1,0]
	v_max_i32_e32 v174, 0, v82
	v_max_i32_e32 v175, 0, v83
	v_log_f32_e32 v200, v200
	v_log_f32_e32 v201, v201
	v_exp_f32_e64 v204, -|v86|
	v_exp_f32_e64 v205, -|v87|
	v_pk_add_f32 v[202:203], v[202:203], v[236:237] op_sel_hi:[1,0]
	v_max_i32_e32 v176, 0, v84
	v_max_i32_e32 v177, 0, v85
	v_log_f32_e32 v202, v202
	v_log_f32_e32 v203, v203
	v_pk_add_f32 v[200:201], v[200:201], v[174:175]
	v_pk_add_f32 v[82:83], v[82:83], v[200:201] neg_lo:[0,1] neg_hi:[0,1]
	v_exp_f32_e64 v206, -|v88|
	v_exp_f32_e64 v207, -|v89|
	v_pk_add_f32 v[204:205], v[204:205], v[236:237] op_sel_hi:[1,0]
	v_max_i32_e32 v174, 0, v86
	v_max_i32_e32 v175, 0, v87
	v_log_f32_e32 v204, v204
	v_log_f32_e32 v205, v205
	v_pk_add_f32 v[202:203], v[202:203], v[176:177]
	v_pk_add_f32 v[84:85], v[84:85], v[202:203] neg_lo:[0,1] neg_hi:[0,1]
	v_exp_f32_e64 v208, -|v90|
	v_exp_f32_e64 v209, -|v91|
	v_pk_add_f32 v[206:207], v[206:207], v[236:237] op_sel_hi:[1,0]
	v_max_i32_e32 v176, 0, v88
	v_max_i32_e32 v177, 0, v89
	v_log_f32_e32 v206, v206
	v_log_f32_e32 v207, v207
	v_pk_add_f32 v[204:205], v[204:205], v[174:175]
	v_pk_add_f32 v[86:87], v[86:87], v[204:205] neg_lo:[0,1] neg_hi:[0,1]
	v_exp_f32_e64 v210, -|v92|
	v_exp_f32_e64 v211, -|v93|
	v_pk_add_f32 v[208:209], v[208:209], v[236:237] op_sel_hi:[1,0]
	v_max_i32_e32 v174, 0, v90
	v_max_i32_e32 v175, 0, v91
	v_log_f32_e32 v208, v208
	v_log_f32_e32 v209, v209
	v_pk_add_f32 v[206:207], v[206:207], v[176:177]
	v_pk_add_f32 v[88:89], v[88:89], v[206:207] neg_lo:[0,1] neg_hi:[0,1]
	v_exp_f32_e64 v212, -|v94|
	v_exp_f32_e64 v213, -|v95|
	v_pk_add_f32 v[210:211], v[210:211], v[236:237] op_sel_hi:[1,0]
	v_max_i32_e32 v176, 0, v92
	v_max_i32_e32 v177, 0, v93
	v_log_f32_e32 v210, v210
	v_log_f32_e32 v211, v211
	v_pk_add_f32 v[208:209], v[208:209], v[174:175]
	v_pk_add_f32 v[90:91], v[90:91], v[208:209] neg_lo:[0,1] neg_hi:[0,1]
	v_exp_f32_e64 v214, -|v96|
	v_exp_f32_e64 v215, -|v97|
	v_pk_add_f32 v[212:213], v[212:213], v[236:237] op_sel_hi:[1,0]
	v_max_i32_e32 v174, 0, v94
	v_max_i32_e32 v175, 0, v95
	v_log_f32_e32 v212, v212
	v_log_f32_e32 v213, v213
	v_pk_add_f32 v[210:211], v[210:211], v[176:177]
	v_pk_add_f32 v[92:93], v[92:93], v[210:211] neg_lo:[0,1] neg_hi:[0,1]
	v_pk_add_f32 v[214:215], v[214:215], v[236:237] op_sel_hi:[1,0]
	v_max_i32_e32 v176, 0, v96
	v_max_i32_e32 v177, 0, v97
	v_log_f32_e32 v214, v214
	v_log_f32_e32 v215, v215
	v_pk_add_f32 v[212:213], v[212:213], v[174:175]
	v_pk_add_f32 v[94:95], v[94:95], v[212:213] neg_lo:[0,1] neg_hi:[0,1]
	v_pk_add_f32 v[214:215], v[214:215], v[176:177]
	v_pk_add_f32 v[96:97], v[96:97], v[214:215] neg_lo:[0,1] neg_hi:[0,1]
	v_pk_add_f32 v[174:175], v[200:201], v[202:203]
	v_add_f32_e32 v216, v174, v175
	v_mov_b32_e32 v220, v216
	v_pk_add_f32 v[176:177], v[204:205], v[206:207]
	v_add_f32_e32 v217, v176, v177
	v_mov_b32_e32 v221, v217
	v_pk_add_f32 v[174:175], v[208:209], v[210:211]
	v_add_f32_e32 v218, v174, v175
	v_mov_b32_e32 v222, v218
	v_pk_add_f32 v[176:177], v[212:213], v[214:215]
	v_add_f32_e32 v219, v176, v177
	v_mov_b32_e32 v223, v219
	s_nop 1
	v_permlane32_swap_b32_e32 v216, v220
	v_permlane32_swap_b32_e32 v217, v221
	v_permlane32_swap_b32_e32 v218, v222
	v_permlane32_swap_b32_e32 v219, v223
	v_add_f32_e32 v216, v216, v220
	v_add_f32_e32 v217, v217, v221
	v_add_f32_e32 v218, v218, v222
	v_add_f32_e32 v219, v219, v223
	v_add_f32_e32 v224, v219, v218
	v_add_f32_e32 v225, v224, v217
	v_add_f32_e32 v183, v225, v216
	v_sub_f32_e32 v182, v172, v183
	v_fma_f32 v233, -v223, v173, v172
	v_sub_f32_e32 v232, v233, v215
	v_sub_f32_e32 v229, v232, v214
	v_sub_f32_e32 v228, v229, v213
	v_pk_add_f32 v[96:97], v[96:97], v[232:233]
	v_pk_add_f32 v[94:95], v[94:95], v[228:229]
	v_exp_f32_e32 v96, v96
	v_exp_f32_e32 v97, v97
	v_exp_f32_e32 v94, v94
	v_exp_f32_e32 v95, v95
	v_sub_f32_e32 v227, v172, v219
	v_fma_f32 v177, -v222, v173, v227
	v_sub_f32_e32 v176, v177, v211
	v_sub_f32_e32 v235, v176, v210
	v_sub_f32_e32 v234, v235, v209
	v_pk_add_f32 v[92:93], v[92:93], v[176:177]
	v_pk_add_f32 v[90:91], v[90:91], v[234:235]
	v_exp_f32_e32 v92, v92
	v_exp_f32_e32 v93, v93
	v_exp_f32_e32 v90, v90
	v_exp_f32_e32 v91, v91
	v_sub_f32_e32 v226, v172, v224
	v_fma_f32 v233, -v221, v173, v226
	v_sub_f32_e32 v232, v233, v207
	v_sub_f32_e32 v229, v232, v206
	v_sub_f32_e32 v228, v229, v205
	v_pk_add_f32 v[88:89], v[88:89], v[232:233]
	v_pk_add_f32 v[86:87], v[86:87], v[228:229]
	v_exp_f32_e32 v88, v88
	v_exp_f32_e32 v89, v89
	v_exp_f32_e32 v86, v86
	v_exp_f32_e32 v87, v87
	v_sub_f32_e32 v227, v172, v225
	v_fma_f32 v177, -v220, v173, v227
	v_sub_f32_e32 v176, v177, v203
	v_sub_f32_e32 v235, v176, v202
	v_sub_f32_e32 v234, v235, v201
	v_pk_add_f32 v[84:85], v[84:85], v[176:177]
	v_pk_add_f32 v[82:83], v[82:83], v[234:235]
	v_exp_f32_e32 v84, v84
	v_exp_f32_e32 v85, v85
	v_exp_f32_e32 v82, v82
	v_exp_f32_e32 v83, v83
	v_add_u32_e32 v199, 32, v159
	v_cmp_gt_i32_e32 vcc, 28, v199
	s_cmp_eq_u64 vcc, 0
	s_cbranch_scc1 .Lstk_nm0
	v_cmp_lt_i32_e64 s[0:1], 0, v199
	v_cmp_lt_i32_e64 s[8:9], 1, v199
	v_cmp_lt_i32_e64 s[10:11], 2, v199
	v_cmp_lt_i32_e64 s[12:13], 3, v199
	v_cndmask_b32_e64 v66, v231, v66, s[0:1]
	v_cndmask_b32_e64 v67, v231, v67, s[8:9]
	v_cndmask_b32_e64 v68, v231, v68, s[10:11]
	v_cndmask_b32_e64 v69, v231, v69, s[12:13]
	v_cmp_lt_i32_e64 s[0:1], 8, v199
	v_cmp_lt_i32_e64 s[8:9], 9, v199
	v_cmp_lt_i32_e64 s[10:11], 10, v199
	v_cmp_lt_i32_e64 s[12:13], 11, v199
	v_cndmask_b32_e64 v70, v231, v70, s[0:1]
	v_cndmask_b32_e64 v71, v231, v71, s[8:9]
	v_cndmask_b32_e64 v72, v231, v72, s[10:11]
	v_cndmask_b32_e64 v73, v231, v73, s[12:13]
	v_cmp_lt_i32_e64 s[0:1], 16, v199
	v_cmp_lt_i32_e64 s[8:9], 17, v199
	v_cmp_lt_i32_e64 s[10:11], 18, v199
	v_cmp_lt_i32_e64 s[12:13], 19, v199
	v_cndmask_b32_e64 v74, v231, v74, s[0:1]
	v_cndmask_b32_e64 v75, v231, v75, s[8:9]
	v_cndmask_b32_e64 v76, v231, v76, s[10:11]
	v_cndmask_b32_e64 v77, v231, v77, s[12:13]
	v_cmp_lt_i32_e64 s[0:1], 24, v199
	v_cmp_lt_i32_e64 s[8:9], 25, v199
	v_cmp_lt_i32_e64 s[10:11], 26, v199
	v_cmp_lt_i32_e64 s[12:13], 27, v199
	v_cndmask_b32_e64 v78, v231, v78, s[0:1]
	v_cndmask_b32_e64 v79, v231, v79, s[8:9]
	v_cndmask_b32_e64 v80, v231, v80, s[10:11]
	v_cndmask_b32_e64 v81, v231, v81, s[12:13]
.Lstk_nm0:
	v_exp_f32_e64 v200, -|v66|
	v_exp_f32_e64 v201, -|v67|
	v_exp_f32_e64 v202, -|v68|
	v_exp_f32_e64 v203, -|v69|
	v_pk_add_f32 v[200:201], v[200:201], v[236:237] op_sel_hi:[1,0]
	v_max_i32_e32 v174, 0, v66
	v_max_i32_e32 v175, 0, v67
	v_log_f32_e32 v200, v200
	v_log_f32_e32 v201, v201
	v_exp_f32_e64 v204, -|v70|
	v_exp_f32_e64 v205, -|v71|
	v_pk_add_f32 v[202:203], v[202:203], v[236:237] op_sel_hi:[1,0]
	v_max_i32_e32 v176, 0, v68
	v_max_i32_e32 v177, 0, v69
	v_log_f32_e32 v202, v202
	v_log_f32_e32 v203, v203
	v_pk_add_f32 v[200:201], v[200:201], v[174:175]
	v_pk_add_f32 v[66:67], v[66:67], v[200:201] neg_lo:[0,1] neg_hi:[0,1]
	v_exp_f32_e64 v206, -|v72|
	v_exp_f32_e64 v207, -|v73|
	v_pk_add_f32 v[204:205], v[204:205], v[236:237] op_sel_hi:[1,0]
	v_max_i32_e32 v174, 0, v70
	v_max_i32_e32 v175, 0, v71
	v_log_f32_e32 v204, v204
	v_log_f32_e32 v205, v205
	v_pk_add_f32 v[202:203], v[202:203], v[176:177]
	v_pk_add_f32 v[68:69], v[68:69], v[202:203] neg_lo:[0,1] neg_hi:[0,1]
	v_exp_f32_e64 v208, -|v74|
	v_exp_f32_e64 v209, -|v75|
	v_pk_add_f32 v[206:207], v[206:207], v[236:237] op_sel_hi:[1,0]
	v_max_i32_e32 v176, 0, v72
	v_max_i32_e32 v177, 0, v73
	v_log_f32_e32 v206, v206
	v_log_f32_e32 v207, v207
	v_pk_add_f32 v[204:205], v[204:205], v[174:175]
	v_pk_add_f32 v[70:71], v[70:71], v[204:205] neg_lo:[0,1] neg_hi:[0,1]
	v_exp_f32_e64 v210, -|v76|
	v_exp_f32_e64 v211, -|v77|
	v_pk_add_f32 v[208:209], v[208:209], v[236:237] op_sel_hi:[1,0]
	v_max_i32_e32 v174, 0, v74
	v_max_i32_e32 v175, 0, v75
	v_log_f32_e32 v208, v208
	v_log_f32_e32 v209, v209
	v_pk_add_f32 v[206:207], v[206:207], v[176:177]
	v_pk_add_f32 v[72:73], v[72:73], v[206:207] neg_lo:[0,1] neg_hi:[0,1]
	v_exp_f32_e64 v212, -|v78|
	v_exp_f32_e64 v213, -|v79|
	v_pk_add_f32 v[210:211], v[210:211], v[236:237] op_sel_hi:[1,0]
	v_max_i32_e32 v176, 0, v76
	v_max_i32_e32 v177, 0, v77
	v_log_f32_e32 v210, v210
	v_log_f32_e32 v211, v211
	v_pk_add_f32 v[208:209], v[208:209], v[174:175]
	v_pk_add_f32 v[74:75], v[74:75], v[208:209] neg_lo:[0,1] neg_hi:[0,1]
	v_exp_f32_e64 v214, -|v80|
	v_exp_f32_e64 v215, -|v81|
	v_pk_add_f32 v[212:213], v[212:213], v[236:237] op_sel_hi:[1,0]
	v_max_i32_e32 v174, 0, v78
	v_max_i32_e32 v175, 0, v79
	v_log_f32_e32 v212, v212
	v_log_f32_e32 v213, v213
	v_pk_add_f32 v[210:211], v[210:211], v[176:177]
	v_pk_add_f32 v[76:77], v[76:77], v[210:211] neg_lo:[0,1] neg_hi:[0,1]
	v_pk_add_f32 v[214:215], v[214:215], v[236:237] op_sel_hi:[1,0]
	v_max_i32_e32 v176, 0, v80
	v_max_i32_e32 v177, 0, v81
	v_log_f32_e32 v214, v214
	v_log_f32_e32 v215, v215
	v_pk_add_f32 v[212:213], v[212:213], v[174:175]
	v_pk_add_f32 v[78:79], v[78:79], v[212:213] neg_lo:[0,1] neg_hi:[0,1]
	v_pk_add_f32 v[214:215], v[214:215], v[176:177]
	v_pk_add_f32 v[80:81], v[80:81], v[214:215] neg_lo:[0,1] neg_hi:[0,1]
	v_pk_add_f32 v[174:175], v[200:201], v[202:203]
	v_add_f32_e32 v216, v174, v175
	v_mov_b32_e32 v220, v216
	v_pk_add_f32 v[176:177], v[204:205], v[206:207]
	v_add_f32_e32 v217, v176, v177
	v_mov_b32_e32 v221, v217
	v_pk_add_f32 v[174:175], v[208:209], v[210:211]
	v_add_f32_e32 v218, v174, v175
	v_mov_b32_e32 v222, v218
	v_pk_add_f32 v[176:177], v[212:213], v[214:215]
	v_add_f32_e32 v219, v176, v177
	v_mov_b32_e32 v223, v219
	s_nop 1
	v_permlane32_swap_b32_e32 v216, v220
	v_permlane32_swap_b32_e32 v217, v221
	v_permlane32_swap_b32_e32 v218, v222
	v_permlane32_swap_b32_e32 v219, v223
	v_add_f32_e32 v216, v216, v220
	v_add_f32_e32 v217, v217, v221
	v_add_f32_e32 v218, v218, v222
	v_add_f32_e32 v219, v219, v223
	v_add_f32_e32 v224, v219, v218
	v_add_f32_e32 v225, v224, v217
	v_add_f32_e32 v230, v225, v216
	v_fma_f32 v233, -v223, v173, v182
	v_sub_f32_e32 v232, v233, v215
	v_sub_f32_e32 v229, v232, v214
	v_sub_f32_e32 v228, v229, v213
	v_pk_add_f32 v[80:81], v[80:81], v[232:233]
	v_pk_add_f32 v[78:79], v[78:79], v[228:229]
	v_exp_f32_e32 v80, v80
	v_exp_f32_e32 v81, v81
	v_exp_f32_e32 v78, v78
	v_exp_f32_e32 v79, v79
	v_sub_f32_e32 v227, v182, v219
	v_fma_f32 v177, -v222, v173, v227
	v_sub_f32_e32 v176, v177, v211
	v_sub_f32_e32 v235, v176, v210
	v_sub_f32_e32 v234, v235, v209
	v_pk_add_f32 v[76:77], v[76:77], v[176:177]
	v_pk_add_f32 v[74:75], v[74:75], v[234:235]
	v_exp_f32_e32 v76, v76
	v_exp_f32_e32 v77, v77
	v_exp_f32_e32 v74, v74
	v_exp_f32_e32 v75, v75
	v_sub_f32_e32 v226, v182, v224
	v_fma_f32 v233, -v221, v173, v226
	v_sub_f32_e32 v232, v233, v207
	v_sub_f32_e32 v229, v232, v206
	v_sub_f32_e32 v228, v229, v205
	v_pk_add_f32 v[72:73], v[72:73], v[232:233]
	v_pk_add_f32 v[70:71], v[70:71], v[228:229]
	v_exp_f32_e32 v72, v72
	v_exp_f32_e32 v73, v73
	v_exp_f32_e32 v70, v70
	v_exp_f32_e32 v71, v71
	v_sub_f32_e32 v227, v182, v225
	v_fma_f32 v177, -v220, v173, v227
	v_sub_f32_e32 v176, v177, v203
	v_sub_f32_e32 v235, v176, v202
	v_sub_f32_e32 v234, v235, v201
	v_pk_add_f32 v[68:69], v[68:69], v[176:177]
	v_pk_add_f32 v[66:67], v[66:67], v[234:235]
	v_exp_f32_e32 v68, v68
	v_exp_f32_e32 v69, v69
	v_exp_f32_e32 v66, v66
	v_exp_f32_e32 v67, v67
	v_add_f32_e64 v173, -v183, -v230
	v_add_u32_e32 v0, v0, v191
	v_cvt_pk_bf16_f32 v66, v66, v67
	v_cvt_pk_bf16_f32 v67, v68, v69
	v_cvt_pk_bf16_f32 v68, v70, v71
	v_cvt_pk_bf16_f32 v69, v72, v73
	v_cvt_pk_bf16_f32 v70, v74, v75
	v_cvt_pk_bf16_f32 v71, v76, v77
	v_cvt_pk_bf16_f32 v72, v78, v79
	v_cvt_pk_bf16_f32 v73, v80, v81
	v_cvt_pk_bf16_f32 v74, v82, v83
	v_cvt_pk_bf16_f32 v75, v84, v85
	v_cvt_pk_bf16_f32 v76, v86, v87
	v_cvt_pk_bf16_f32 v77, v88, v89
	v_cvt_pk_bf16_f32 v78, v90, v91
	v_cvt_pk_bf16_f32 v79, v92, v93
	v_cvt_pk_bf16_f32 v80, v94, v95
	v_cvt_pk_bf16_f32 v81, v96, v97
	ds_read_b128 v[82:85], v0 offset:17408
	ds_read_b128 v[86:89], v0 offset:22016
	ds_read_b128 v[90:93], v0 offset:26624
	ds_read_b128 v[94:97], v0 offset:31232
	s_setprio 1
	s_waitcnt lgkmcnt(3)
	v_mfma_f32_32x32x16_bf16 v[50:65], v[82:85], v[66:69], v[50:65]
	s_waitcnt lgkmcnt(2)
	v_mfma_f32_32x32x16_bf16 v[34:49], v[86:89], v[66:69], v[34:49]
	s_waitcnt lgkmcnt(1)
	v_mfma_f32_32x32x16_bf16 v[18:33], v[90:93], v[66:69], v[18:33]
	s_waitcnt lgkmcnt(0)
	v_mfma_f32_32x32x16_bf16 v[2:17], v[94:97], v[66:69], v[2:17]
	s_setprio 0
	ds_read_b128 v[66:69], v0 offset:17440
	ds_read_b128 v[82:85], v0 offset:22048
	ds_read_b128 v[86:89], v0 offset:26656
	ds_read_b128 v[90:93], v0 offset:31264
	s_setprio 1
	s_waitcnt lgkmcnt(3)
	v_mfma_f32_32x32x16_bf16 v[50:65], v[66:69], v[70:73], v[50:65]
	s_waitcnt lgkmcnt(2)
	v_mfma_f32_32x32x16_bf16 v[34:49], v[82:85], v[70:73], v[34:49]
	s_waitcnt lgkmcnt(1)
	v_mfma_f32_32x32x16_bf16 v[18:33], v[86:89], v[70:73], v[18:33]
	s_waitcnt lgkmcnt(0)
	v_mfma_f32_32x32x16_bf16 v[2:17], v[90:93], v[70:73], v[2:17]
	s_setprio 0
	ds_read_b128 v[66:69], v0 offset:17472
	ds_read_b128 v[70:73], v0 offset:22080
	ds_read_b128 v[82:85], v0 offset:26688
	ds_read_b128 v[86:89], v0 offset:31296
	s_setprio 1
	s_waitcnt lgkmcnt(3)
	v_mfma_f32_32x32x16_bf16 v[50:65], v[66:69], v[74:77], v[50:65]
	s_waitcnt lgkmcnt(2)
	v_mfma_f32_32x32x16_bf16 v[34:49], v[70:73], v[74:77], v[34:49]
	s_waitcnt lgkmcnt(1)
	v_mfma_f32_32x32x16_bf16 v[18:33], v[82:85], v[74:77], v[18:33]
	s_waitcnt lgkmcnt(0)
	v_mfma_f32_32x32x16_bf16 v[2:17], v[86:89], v[74:77], v[2:17]
	s_setprio 0
	ds_read_b128 v[66:69], v0 offset:17504
	ds_read_b128 v[70:73], v0 offset:22112
	ds_read_b128 v[74:77], v0 offset:26720
	ds_read_b128 v[82:85], v0 offset:31328
	s_setprio 1
	s_waitcnt lgkmcnt(3)
	v_mfma_f32_32x32x16_bf16 v[50:65], v[66:69], v[78:81], v[50:65]
	s_waitcnt lgkmcnt(2)
	v_mfma_f32_32x32x16_bf16 v[34:49], v[70:73], v[78:81], v[34:49]
	s_waitcnt lgkmcnt(1)
	v_mfma_f32_32x32x16_bf16 v[18:33], v[74:77], v[78:81], v[18:33]
	s_waitcnt lgkmcnt(0)
	v_mfma_f32_32x32x16_bf16 v[2:17], v[82:85], v[78:81], v[2:17]
	s_setprio 0
	v_add_f32_e32 v172, v172, v173

.LBB0_67:
	s_mul_i32 s0, s49, 0x8c00
	s_add_i32 s47, s0, 0
	v_add3_u32 v217, s47, v209, v210
	v_lshrrev_b32_e32 v218, v186, v202
	v_lshrrev_b32_e32 v203, v186, v203
	s_and_saveexec_b64 s[0:1], s[6:7]
	s_xor_b64 s[0:1], exec, s[0:1]
	s_cbranch_execz .LBB0_71
	v_bfe_i32 v83, v218, 0, 1
	v_bfe_i32 v174, v203, 0, 1
	v_bfe_i32 v67, v218, 1, 1
	v_bfe_i32 v175, v203, 1, 1
	v_bfe_i32 v68, v218, 2, 1
	v_bfe_i32 v84, v203, 2, 1
	v_bfe_i32 v69, v218, 3, 1
	v_bfe_i32 v85, v203, 3, 1
	v_bfe_i32 v70, v218, 8, 1
	v_bfe_i32 v86, v203, 8, 1
	v_bfe_i32 v71, v218, 9, 1
	v_bfe_i32 v87, v203, 9, 1
	v_bfe_i32 v72, v218, 10, 1
	v_bfe_i32 v88, v203, 10, 1
	v_bfe_i32 v73, v218, 11, 1
	v_bfe_i32 v89, v203, 11, 1
	v_bfe_i32 v74, v218, 16, 1
	v_bfe_i32 v90, v203, 16, 1
	v_bfe_i32 v75, v218, 17, 1
	v_bfe_i32 v91, v203, 17, 1
	v_bfe_i32 v76, v218, 18, 1
	v_bfe_i32 v92, v203, 18, 1
	v_bfe_i32 v77, v218, 19, 1
	v_bfe_i32 v93, v203, 19, 1
	v_bfe_i32 v78, v218, 24, 1
	v_bfe_i32 v94, v203, 24, 1
	v_bfe_i32 v79, v218, 25, 1
	v_bfe_i32 v95, v203, 25, 1
	v_bfe_i32 v80, v218, 26, 1
	v_bfe_i32 v96, v203, 26, 1
	v_bfe_i32 v66, v218, 27, 1
	v_bfe_i32 v82, v203, 27, 1
	s_nop 0
	v_bfi_b32 v79, v79, v230, v231
	v_bfi_b32 v81, v66, v230, v231
	v_bfi_b32 v66, v83, v230, v231
	v_bfi_b32 v97, v82, v230, v231
	v_bfi_b32 v83, v175, v230, v231
	v_bfi_b32 v82, v174, v230, v231
	ds_read_b128 v[218:221], v217 offset:8704
	ds_read_b128 v[222:225], v217
	ds_read_b128 v[226:229], v217 offset:32
	ds_read_b128 v[232:235], v217 offset:8736
	ds_read_b128 v[236:239], v217 offset:64
	ds_read_b128 v[248:251], v217 offset:8768
	ds_read_b128 v[240:243], v217 offset:96
	ds_read_b128 v[174:177], v217 offset:8800
	v_bfi_b32 v80, v80, v230, v231
	v_bfi_b32 v78, v78, v230, v231
	v_bfi_b32 v77, v77, v230, v231
	v_bfi_b32 v76, v76, v230, v231
	v_bfi_b32 v75, v75, v230, v231
	v_bfi_b32 v74, v74, v230, v231
	v_bfi_b32 v73, v73, v230, v231
	v_bfi_b32 v72, v72, v230, v231
	v_bfi_b32 v71, v71, v230, v231
	v_bfi_b32 v70, v70, v230, v231
	v_bfi_b32 v69, v69, v230, v231
	v_bfi_b32 v68, v68, v230, v231
	v_bfi_b32 v67, v67, v230, v231
	v_bfi_b32 v96, v96, v230, v231
	v_bfi_b32 v95, v95, v230, v231
	v_bfi_b32 v94, v94, v230, v231
	v_bfi_b32 v93, v93, v230, v231
	v_bfi_b32 v92, v92, v230, v231
	v_bfi_b32 v91, v91, v230, v231
	v_bfi_b32 v90, v90, v230, v231
	v_bfi_b32 v89, v89, v230, v231
	v_bfi_b32 v88, v88, v230, v231
	v_bfi_b32 v87, v87, v230, v231
	v_bfi_b32 v86, v86, v230, v231
	v_bfi_b32 v85, v85, v230, v231
	v_bfi_b32 v84, v84, v230, v231
	s_setprio 1
	s_waitcnt lgkmcnt(6)
	v_mfma_f32_32x32x16_bf16 v[66:81], v[222:225], v[98:101], v[66:81]
	v_mfma_f32_32x32x16_bf16 v[82:97], v[218:221], v[98:101], v[82:97]
	s_waitcnt lgkmcnt(5)
	v_mfma_f32_32x32x16_bf16 v[66:81], v[226:229], v[102:105], v[66:81]
	s_waitcnt lgkmcnt(4)
	v_mfma_f32_32x32x16_bf16 v[82:97], v[232:235], v[102:105], v[82:97]
	s_waitcnt lgkmcnt(3)
	v_mfma_f32_32x32x16_bf16 v[66:81], v[236:239], v[106:109], v[66:81]
	s_waitcnt lgkmcnt(2)
	v_mfma_f32_32x32x16_bf16 v[82:97], v[248:251], v[106:109], v[82:97]
	s_waitcnt lgkmcnt(1)
	v_mfma_f32_32x32x16_bf16 v[66:81], v[240:243], v[110:113], v[66:81]
	s_waitcnt lgkmcnt(0)
	v_mfma_f32_32x32x16_bf16 v[82:97], v[174:177], v[110:113], v[82:97]
	s_setprio 0
	ds_read_b128 v[174:177], v217 offset:128
	ds_read_b128 v[218:221], v217 offset:160
	ds_read_b128 v[222:225], v217 offset:8832
	ds_read_b128 v[226:229], v217 offset:8864
	ds_read_b128 v[232:235], v217 offset:192
	ds_read_b128 v[236:239], v217 offset:224
	ds_read_b128 v[240:243], v217 offset:8896
	ds_read_b128 v[248:251], v217 offset:8928
	s_setprio 1
	s_waitcnt lgkmcnt(7)
	v_mfma_f32_32x32x16_bf16 v[66:81], v[174:177], v[114:117], v[66:81]
	s_waitcnt lgkmcnt(5)
	v_mfma_f32_32x32x16_bf16 v[82:97], v[222:225], v[114:117], v[82:97]
	v_mfma_f32_32x32x16_bf16 v[66:81], v[218:221], v[118:121], v[66:81]
	s_waitcnt lgkmcnt(4)
	v_mfma_f32_32x32x16_bf16 v[82:97], v[226:229], v[118:121], v[82:97]
	s_waitcnt lgkmcnt(3)
	v_mfma_f32_32x32x16_bf16 v[66:81], v[232:235], v[122:125], v[66:81]
	s_waitcnt lgkmcnt(1)
	v_mfma_f32_32x32x16_bf16 v[82:97], v[240:243], v[122:125], v[82:97]
	v_mfma_f32_32x32x16_bf16 v[66:81], v[236:239], v[126:129], v[66:81]
	s_waitcnt lgkmcnt(0)
	v_mfma_f32_32x32x16_bf16 v[82:97], v[248:251], v[126:129], v[82:97]
	s_setprio 0
	v_max3_f32 v174, v231, v66, v82
	s_nop 0
	v_max3_f32 v174, v174, v67, v83
	s_nop 0
	v_max3_f32 v174, v174, v68, v84
	s_nop 0
	v_max3_f32 v174, v174, v69, v85
	s_nop 0
	v_max3_f32 v174, v174, v70, v86
	s_nop 0
	v_max3_f32 v174, v174, v71, v87
	s_nop 0
	v_max3_f32 v174, v174, v72, v88
	s_nop 0
	v_max3_f32 v174, v174, v73, v89
	s_nop 0
	v_max3_f32 v174, v174, v74, v90
	s_nop 0
	v_max3_f32 v174, v174, v75, v91
	s_nop 0
	v_max3_f32 v174, v174, v76, v92
	s_nop 0
	v_max3_f32 v174, v174, v77, v93
	s_nop 0
	v_max3_f32 v174, v174, v78, v94
	s_nop 0
	v_max3_f32 v174, v174, v79, v95
	s_nop 0
	v_max3_f32 v174, v174, v80, v96
	s_nop 0
	v_max3_f32 v174, v174, v81, v97
	s_nop 0
	v_mov_b32_e32 v175, v174
	s_nop 1
	v_permlane32_swap_b32_e32 v174, v175
	v_max_f32_e32 v174, v174, v175
	v_cmp_gt_f32_e32 vcc, v174, v245
	s_cmp_eq_u64 vcc, 0
	s_cbranch_scc1 .Lsmf_0
	v_cndmask_b32_e32 v203, 0, v174, vcc
	v_mov_b32_e32 v175, 0x41000000
	v_cndmask_b32_e32 v245, v245, v175, vcc
	v_sub_f32_e32 v230, v230, v203
	v_max_f32_e32 v175, 0, v203
	v_exp_f32_e64 v202, -v175
	s_nop 0
	v_pk_mul_f32 v[64:65], v[64:65], v[202:203] op_sel_hi:[1,0]
	v_pk_mul_f32 v[62:63], v[62:63], v[202:203] op_sel_hi:[1,0]
	v_pk_mul_f32 v[60:61], v[60:61], v[202:203] op_sel_hi:[1,0]
	v_pk_mul_f32 v[58:59], v[58:59], v[202:203] op_sel_hi:[1,0]
	v_pk_mul_f32 v[56:57], v[56:57], v[202:203] op_sel_hi:[1,0]
	v_pk_mul_f32 v[54:55], v[54:55], v[202:203] op_sel_hi:[1,0]
	v_pk_mul_f32 v[52:53], v[52:53], v[202:203] op_sel_hi:[1,0]
	v_pk_mul_f32 v[50:51], v[50:51], v[202:203] op_sel_hi:[1,0]
	v_pk_mul_f32 v[48:49], v[48:49], v[202:203] op_sel_hi:[1,0]
	v_pk_mul_f32 v[46:47], v[46:47], v[202:203] op_sel_hi:[1,0]
	v_pk_mul_f32 v[44:45], v[44:45], v[202:203] op_sel_hi:[1,0]
	v_pk_mul_f32 v[42:43], v[42:43], v[202:203] op_sel_hi:[1,0]
	v_pk_mul_f32 v[40:41], v[40:41], v[202:203] op_sel_hi:[1,0]
	v_pk_mul_f32 v[38:39], v[38:39], v[202:203] op_sel_hi:[1,0]
	v_pk_mul_f32 v[36:37], v[36:37], v[202:203] op_sel_hi:[1,0]
	v_pk_mul_f32 v[34:35], v[34:35], v[202:203] op_sel_hi:[1,0]
	v_pk_mul_f32 v[32:33], v[32:33], v[202:203] op_sel_hi:[1,0]
	v_pk_mul_f32 v[30:31], v[30:31], v[202:203] op_sel_hi:[1,0]
	v_pk_mul_f32 v[28:29], v[28:29], v[202:203] op_sel_hi:[1,0]
	v_pk_mul_f32 v[26:27], v[26:27], v[202:203] op_sel_hi:[1,0]
	v_pk_mul_f32 v[24:25], v[24:25], v[202:203] op_sel_hi:[1,0]
	v_pk_mul_f32 v[22:23], v[22:23], v[202:203] op_sel_hi:[1,0]
	v_pk_mul_f32 v[20:21], v[20:21], v[202:203] op_sel_hi:[1,0]
	v_pk_mul_f32 v[18:19], v[18:19], v[202:203] op_sel_hi:[1,0]
	v_pk_mul_f32 v[16:17], v[16:17], v[202:203] op_sel_hi:[1,0]
	v_pk_mul_f32 v[14:15], v[14:15], v[202:203] op_sel_hi:[1,0]
	v_pk_mul_f32 v[12:13], v[12:13], v[202:203] op_sel_hi:[1,0]
	v_pk_mul_f32 v[10:11], v[10:11], v[202:203] op_sel_hi:[1,0]
	v_pk_mul_f32 v[8:9], v[8:9], v[202:203] op_sel_hi:[1,0]
	v_pk_mul_f32 v[6:7], v[6:7], v[202:203] op_sel_hi:[1,0]
	v_pk_mul_f32 v[4:5], v[4:5], v[202:203] op_sel_hi:[1,0]
	v_pk_mul_f32 v[2:3], v[2:3], v[202:203] op_sel_hi:[1,0]

.LBB0_77:
	v_bfe_i32 v83, v218, 0, 1
	v_bfe_i32 v174, v203, 0, 1
	v_bfe_i32 v67, v218, 1, 1
	v_bfe_i32 v175, v203, 1, 1
	v_bfe_i32 v68, v218, 2, 1
	v_bfe_i32 v84, v203, 2, 1
	v_bfe_i32 v69, v218, 3, 1
	v_bfe_i32 v85, v203, 3, 1
	v_bfe_i32 v70, v218, 8, 1
	v_bfe_i32 v86, v203, 8, 1
	v_bfe_i32 v71, v218, 9, 1
	v_bfe_i32 v87, v203, 9, 1
	v_bfe_i32 v72, v218, 10, 1
	v_bfe_i32 v88, v203, 10, 1
	v_bfe_i32 v73, v218, 11, 1
	v_bfe_i32 v89, v203, 11, 1
	v_bfe_i32 v74, v218, 16, 1
	v_bfe_i32 v90, v203, 16, 1
	v_bfe_i32 v75, v218, 17, 1
	v_bfe_i32 v91, v203, 17, 1
	v_bfe_i32 v76, v218, 18, 1
	v_bfe_i32 v92, v203, 18, 1
	v_bfe_i32 v77, v218, 19, 1
	v_bfe_i32 v93, v203, 19, 1
	v_bfe_i32 v78, v218, 24, 1
	v_bfe_i32 v94, v203, 24, 1
	v_bfe_i32 v79, v218, 25, 1
	v_bfe_i32 v95, v203, 25, 1
	v_bfe_i32 v80, v218, 26, 1
	v_bfe_i32 v96, v203, 26, 1
	v_bfe_i32 v66, v218, 27, 1
	v_bfe_i32 v82, v203, 27, 1
	s_nop 0
	v_bfi_b32 v79, v79, v230, v231
	v_bfi_b32 v81, v66, v230, v231
	v_bfi_b32 v66, v83, v230, v231
	v_bfi_b32 v97, v82, v230, v231
	v_bfi_b32 v83, v175, v230, v231
	v_bfi_b32 v82, v174, v230, v231
	ds_read_b128 v[174:177], v217 offset:8704
	ds_read_b128 v[218:221], v217
	ds_read_b128 v[222:225], v217 offset:32
	ds_read_b128 v[226:229], v217 offset:8736
	ds_read_b128 v[232:235], v217 offset:64
	ds_read_b128 v[236:239], v217 offset:8768
	ds_read_b128 v[240:243], v217 offset:96
	ds_read_b128 v[248:251], v217 offset:8800
	v_bfi_b32 v80, v80, v230, v231
	v_bfi_b32 v78, v78, v230, v231
	v_bfi_b32 v77, v77, v230, v231
	v_bfi_b32 v76, v76, v230, v231
	v_bfi_b32 v75, v75, v230, v231
	v_bfi_b32 v74, v74, v230, v231
	v_bfi_b32 v73, v73, v230, v231
	v_bfi_b32 v72, v72, v230, v231
	v_bfi_b32 v71, v71, v230, v231
	v_bfi_b32 v70, v70, v230, v231
	v_bfi_b32 v69, v69, v230, v231
	v_bfi_b32 v68, v68, v230, v231
	v_bfi_b32 v67, v67, v230, v231
	v_bfi_b32 v96, v96, v230, v231
	v_bfi_b32 v95, v95, v230, v231
	v_bfi_b32 v94, v94, v230, v231
	v_bfi_b32 v93, v93, v230, v231
	v_bfi_b32 v92, v92, v230, v231
	v_bfi_b32 v91, v91, v230, v231
	v_bfi_b32 v90, v90, v230, v231
	v_bfi_b32 v89, v89, v230, v231
	v_bfi_b32 v88, v88, v230, v231
	v_bfi_b32 v87, v87, v230, v231
	v_bfi_b32 v86, v86, v230, v231
	v_bfi_b32 v85, v85, v230, v231
	v_bfi_b32 v84, v84, v230, v231
	s_setprio 1
	s_waitcnt lgkmcnt(6)
	v_mfma_f32_32x32x16_bf16 v[66:81], v[218:221], v[98:101], v[66:81]
	v_mfma_f32_32x32x16_bf16 v[82:97], v[174:177], v[98:101], v[82:97]
	s_waitcnt lgkmcnt(5)
	v_mfma_f32_32x32x16_bf16 v[66:81], v[222:225], v[102:105], v[66:81]
	s_waitcnt lgkmcnt(4)
	v_mfma_f32_32x32x16_bf16 v[82:97], v[226:229], v[102:105], v[82:97]
	s_waitcnt lgkmcnt(3)
	v_mfma_f32_32x32x16_bf16 v[66:81], v[232:235], v[106:109], v[66:81]
	s_waitcnt lgkmcnt(2)
	v_mfma_f32_32x32x16_bf16 v[82:97], v[236:239], v[106:109], v[82:97]
	s_waitcnt lgkmcnt(1)
	v_mfma_f32_32x32x16_bf16 v[66:81], v[240:243], v[110:113], v[66:81]
	s_waitcnt lgkmcnt(0)
	v_mfma_f32_32x32x16_bf16 v[82:97], v[248:251], v[110:113], v[82:97]
	s_setprio 0
	ds_read_b128 v[174:177], v217 offset:128
	ds_read_b128 v[218:221], v217 offset:160
	ds_read_b128 v[222:225], v217 offset:8832
	ds_read_b128 v[226:229], v217 offset:8864
	ds_read_b128 v[232:235], v217 offset:192
	ds_read_b128 v[236:239], v217 offset:224
	ds_read_b128 v[240:243], v217 offset:8896
	ds_read_b128 v[248:251], v217 offset:8928
	s_setprio 1
	s_waitcnt lgkmcnt(7)
	v_mfma_f32_32x32x16_bf16 v[66:81], v[174:177], v[114:117], v[66:81]
	s_waitcnt lgkmcnt(5)
	v_mfma_f32_32x32x16_bf16 v[82:97], v[222:225], v[114:117], v[82:97]
	v_mfma_f32_32x32x16_bf16 v[66:81], v[218:221], v[118:121], v[66:81]
	s_waitcnt lgkmcnt(4)
	v_mfma_f32_32x32x16_bf16 v[82:97], v[226:229], v[118:121], v[82:97]
	s_waitcnt lgkmcnt(3)
	v_mfma_f32_32x32x16_bf16 v[66:81], v[232:235], v[122:125], v[66:81]
	s_waitcnt lgkmcnt(1)
	v_mfma_f32_32x32x16_bf16 v[82:97], v[240:243], v[122:125], v[82:97]
	v_mfma_f32_32x32x16_bf16 v[66:81], v[236:239], v[126:129], v[66:81]
	s_waitcnt lgkmcnt(0)
	v_mfma_f32_32x32x16_bf16 v[82:97], v[248:251], v[126:129], v[82:97]
	s_setprio 0

.LBB0_90:
	v_bfe_i32 v83, v218, 0, 1
	v_bfe_i32 v174, v205, 0, 1
	v_bfe_i32 v67, v218, 1, 1
	v_bfe_i32 v175, v205, 1, 1
	v_bfe_i32 v68, v218, 2, 1
	v_bfe_i32 v84, v205, 2, 1
	v_bfe_i32 v69, v218, 3, 1
	v_bfe_i32 v85, v205, 3, 1
	v_bfe_i32 v70, v218, 8, 1
	v_bfe_i32 v86, v205, 8, 1
	v_bfe_i32 v71, v218, 9, 1
	v_bfe_i32 v87, v205, 9, 1
	v_bfe_i32 v72, v218, 10, 1
	v_bfe_i32 v88, v205, 10, 1
	v_bfe_i32 v73, v218, 11, 1
	v_bfe_i32 v89, v205, 11, 1
	v_bfe_i32 v74, v218, 16, 1
	v_bfe_i32 v90, v205, 16, 1
	v_bfe_i32 v75, v218, 17, 1
	v_bfe_i32 v91, v205, 17, 1
	v_bfe_i32 v76, v218, 18, 1
	v_bfe_i32 v92, v205, 18, 1
	v_bfe_i32 v77, v218, 19, 1
	v_bfe_i32 v93, v205, 19, 1
	v_bfe_i32 v78, v218, 24, 1
	v_bfe_i32 v94, v205, 24, 1
	v_bfe_i32 v79, v218, 25, 1
	v_bfe_i32 v95, v205, 25, 1
	v_bfe_i32 v80, v218, 26, 1
	v_bfe_i32 v96, v205, 26, 1
	v_bfe_i32 v66, v218, 27, 1
	v_bfe_i32 v82, v205, 27, 1
	s_nop 0
	v_bfi_b32 v79, v79, v230, v231
	v_bfi_b32 v81, v66, v230, v231
	v_bfi_b32 v66, v83, v230, v231
	v_bfi_b32 v97, v82, v230, v231
	v_bfi_b32 v83, v175, v230, v231
	v_bfi_b32 v82, v174, v230, v231
	ds_read_b128 v[174:177], v217 offset:8704
	ds_read_b128 v[218:221], v217
	ds_read_b128 v[222:225], v217 offset:32
	ds_read_b128 v[226:229], v217 offset:8736
	ds_read_b128 v[232:235], v217 offset:64
	ds_read_b128 v[236:239], v217 offset:8768
	ds_read_b128 v[240:243], v217 offset:96
	ds_read_b128 v[248:251], v217 offset:8800
	v_bfi_b32 v80, v80, v230, v231
	v_bfi_b32 v78, v78, v230, v231
	v_bfi_b32 v77, v77, v230, v231
	v_bfi_b32 v76, v76, v230, v231
	v_bfi_b32 v75, v75, v230, v231
	v_bfi_b32 v74, v74, v230, v231
	v_bfi_b32 v73, v73, v230, v231
	v_bfi_b32 v72, v72, v230, v231
	v_bfi_b32 v71, v71, v230, v231
	v_bfi_b32 v70, v70, v230, v231
	v_bfi_b32 v69, v69, v230, v231
	v_bfi_b32 v68, v68, v230, v231
	v_bfi_b32 v67, v67, v230, v231
	v_bfi_b32 v96, v96, v230, v231
	v_bfi_b32 v95, v95, v230, v231
	v_bfi_b32 v94, v94, v230, v231
	v_bfi_b32 v93, v93, v230, v231
	v_bfi_b32 v92, v92, v230, v231
	v_bfi_b32 v91, v91, v230, v231
	v_bfi_b32 v90, v90, v230, v231
	v_bfi_b32 v89, v89, v230, v231
	v_bfi_b32 v88, v88, v230, v231
	v_bfi_b32 v87, v87, v230, v231
	v_bfi_b32 v86, v86, v230, v231
	v_bfi_b32 v85, v85, v230, v231
	v_bfi_b32 v84, v84, v230, v231
	s_setprio 1
	s_waitcnt lgkmcnt(6)
	v_mfma_f32_32x32x16_bf16 v[66:81], v[218:221], v[98:101], v[66:81]
	v_mfma_f32_32x32x16_bf16 v[82:97], v[174:177], v[98:101], v[82:97]
	s_waitcnt lgkmcnt(5)
	v_mfma_f32_32x32x16_bf16 v[66:81], v[222:225], v[102:105], v[66:81]
	s_waitcnt lgkmcnt(4)
	v_mfma_f32_32x32x16_bf16 v[82:97], v[226:229], v[102:105], v[82:97]
	s_waitcnt lgkmcnt(3)
	v_mfma_f32_32x32x16_bf16 v[66:81], v[232:235], v[106:109], v[66:81]
	s_waitcnt lgkmcnt(2)
	v_mfma_f32_32x32x16_bf16 v[82:97], v[236:239], v[106:109], v[82:97]
	s_waitcnt lgkmcnt(1)
	v_mfma_f32_32x32x16_bf16 v[66:81], v[240:243], v[110:113], v[66:81]
	s_waitcnt lgkmcnt(0)
	v_mfma_f32_32x32x16_bf16 v[82:97], v[248:251], v[110:113], v[82:97]
	s_setprio 0
	ds_read_b128 v[174:177], v217 offset:128
	ds_read_b128 v[218:221], v217 offset:160
	ds_read_b128 v[222:225], v217 offset:8832
	ds_read_b128 v[226:229], v217 offset:8864
	ds_read_b128 v[232:235], v217 offset:192
	ds_read_b128 v[236:239], v217 offset:224
	ds_read_b128 v[240:243], v217 offset:8896
	ds_read_b128 v[248:251], v217 offset:8928
	s_setprio 1
	s_waitcnt lgkmcnt(7)
	v_mfma_f32_32x32x16_bf16 v[66:81], v[174:177], v[114:117], v[66:81]
	s_waitcnt lgkmcnt(5)
	v_mfma_f32_32x32x16_bf16 v[82:97], v[222:225], v[114:117], v[82:97]
	v_mfma_f32_32x32x16_bf16 v[66:81], v[218:221], v[118:121], v[66:81]
	s_waitcnt lgkmcnt(4)
	v_mfma_f32_32x32x16_bf16 v[82:97], v[226:229], v[118:121], v[82:97]
	s_waitcnt lgkmcnt(3)
	v_mfma_f32_32x32x16_bf16 v[66:81], v[232:235], v[122:125], v[66:81]
	s_waitcnt lgkmcnt(1)
	v_mfma_f32_32x32x16_bf16 v[82:97], v[240:243], v[122:125], v[82:97]
	v_mfma_f32_32x32x16_bf16 v[66:81], v[236:239], v[126:129], v[66:81]
	s_waitcnt lgkmcnt(0)
	v_mfma_f32_32x32x16_bf16 v[82:97], v[248:251], v[126:129], v[82:97]
	s_setprio 0
	v_max3_f32 v174, v231, v66, v82
	s_nop 0
	v_max3_f32 v174, v174, v67, v83
	s_nop 0
	v_max3_f32 v174, v174, v68, v84
	s_nop 0
	v_max3_f32 v174, v174, v69, v85
	s_nop 0
	v_max3_f32 v174, v174, v70, v86
	s_nop 0
	v_max3_f32 v174, v174, v71, v87
	s_nop 0
	v_max3_f32 v174, v174, v72, v88
	s_nop 0
	v_max3_f32 v174, v174, v73, v89
	s_nop 0
	v_max3_f32 v174, v174, v74, v90
	s_nop 0
	v_max3_f32 v174, v174, v75, v91
	s_nop 0
	v_max3_f32 v174, v174, v76, v92
	s_nop 0
	v_max3_f32 v174, v174, v77, v93
	s_nop 0
	v_max3_f32 v174, v174, v78, v94
	s_nop 0
	v_max3_f32 v174, v174, v79, v95
	s_nop 0
	v_max3_f32 v174, v174, v80, v96
	s_nop 0
	v_max3_f32 v174, v174, v81, v97
	s_nop 0
	v_mov_b32_e32 v175, v174
	s_nop 1
	v_permlane32_swap_b32_e32 v174, v175
	v_max_f32_e32 v174, v174, v175
	v_cmp_gt_f32_e32 vcc, v174, v245
	s_cmp_eq_u64 vcc, 0
	s_cbranch_scc1 .Lsmf_2
	v_cndmask_b32_e32 v193, 0, v174, vcc
	v_mov_b32_e32 v175, 0x41000000
	v_cndmask_b32_e32 v245, v245, v175, vcc
	v_sub_f32_e32 v230, v230, v193
	v_max_f32_e32 v175, 0, v193
	v_exp_f32_e64 v204, -v175
	s_nop 0
	v_pk_mul_f32 v[64:65], v[64:65], v[204:205] op_sel_hi:[1,0]
	v_pk_mul_f32 v[62:63], v[62:63], v[204:205] op_sel_hi:[1,0]
	v_pk_mul_f32 v[60:61], v[60:61], v[204:205] op_sel_hi:[1,0]
	v_pk_mul_f32 v[58:59], v[58:59], v[204:205] op_sel_hi:[1,0]
	v_pk_mul_f32 v[56:57], v[56:57], v[204:205] op_sel_hi:[1,0]
	v_pk_mul_f32 v[54:55], v[54:55], v[204:205] op_sel_hi:[1,0]
	v_pk_mul_f32 v[52:53], v[52:53], v[204:205] op_sel_hi:[1,0]
	v_pk_mul_f32 v[50:51], v[50:51], v[204:205] op_sel_hi:[1,0]
	v_pk_mul_f32 v[48:49], v[48:49], v[204:205] op_sel_hi:[1,0]
	v_pk_mul_f32 v[46:47], v[46:47], v[204:205] op_sel_hi:[1,0]
	v_pk_mul_f32 v[44:45], v[44:45], v[204:205] op_sel_hi:[1,0]
	v_pk_mul_f32 v[42:43], v[42:43], v[204:205] op_sel_hi:[1,0]
	v_pk_mul_f32 v[40:41], v[40:41], v[204:205] op_sel_hi:[1,0]
	v_pk_mul_f32 v[38:39], v[38:39], v[204:205] op_sel_hi:[1,0]
	v_pk_mul_f32 v[36:37], v[36:37], v[204:205] op_sel_hi:[1,0]
	v_pk_mul_f32 v[34:35], v[34:35], v[204:205] op_sel_hi:[1,0]
	v_pk_mul_f32 v[32:33], v[32:33], v[204:205] op_sel_hi:[1,0]
	v_pk_mul_f32 v[30:31], v[30:31], v[204:205] op_sel_hi:[1,0]
	v_pk_mul_f32 v[28:29], v[28:29], v[204:205] op_sel_hi:[1,0]
	v_pk_mul_f32 v[26:27], v[26:27], v[204:205] op_sel_hi:[1,0]
	v_pk_mul_f32 v[24:25], v[24:25], v[204:205] op_sel_hi:[1,0]
	v_pk_mul_f32 v[22:23], v[22:23], v[204:205] op_sel_hi:[1,0]
	v_pk_mul_f32 v[20:21], v[20:21], v[204:205] op_sel_hi:[1,0]
	v_pk_mul_f32 v[18:19], v[18:19], v[204:205] op_sel_hi:[1,0]
	v_pk_mul_f32 v[16:17], v[16:17], v[204:205] op_sel_hi:[1,0]
	v_pk_mul_f32 v[14:15], v[14:15], v[204:205] op_sel_hi:[1,0]
	v_pk_mul_f32 v[12:13], v[12:13], v[204:205] op_sel_hi:[1,0]
	v_pk_mul_f32 v[10:11], v[10:11], v[204:205] op_sel_hi:[1,0]
	v_pk_mul_f32 v[8:9], v[8:9], v[204:205] op_sel_hi:[1,0]
	v_pk_mul_f32 v[6:7], v[6:7], v[204:205] op_sel_hi:[1,0]
	v_pk_mul_f32 v[4:5], v[4:5], v[204:205] op_sel_hi:[1,0]
	v_pk_mul_f32 v[2:3], v[2:3], v[204:205] op_sel_hi:[1,0]

.Lsmj_3:
	v_add3_u32 v174, s47, v210, v211
	v_cvt_pk_bf16_f32 v66, v66, v67
	v_cvt_pk_bf16_f32 v67, v68, v69
	v_cvt_pk_bf16_f32 v68, v70, v71
	v_cvt_pk_bf16_f32 v69, v72, v73
	v_cvt_pk_bf16_f32 v70, v74, v75
	v_cvt_pk_bf16_f32 v71, v76, v77
	v_cvt_pk_bf16_f32 v72, v78, v79
	v_cvt_pk_bf16_f32 v73, v80, v81
	v_cvt_pk_bf16_f32 v74, v82, v83
	v_cvt_pk_bf16_f32 v75, v84, v85
	v_cvt_pk_bf16_f32 v76, v86, v87
	v_cvt_pk_bf16_f32 v77, v88, v89
	v_cvt_pk_bf16_f32 v78, v90, v91
	v_cvt_pk_bf16_f32 v79, v92, v93
	v_cvt_pk_bf16_f32 v80, v94, v95
	v_cvt_pk_bf16_f32 v81, v96, v97
	ds_read_b128 v[82:85], v174 offset:17408
	ds_read_b128 v[86:89], v174 offset:22016
	ds_read_b128 v[90:93], v174 offset:26624
	ds_read_b128 v[94:97], v174 offset:31232
	v_fmac_f32_e32 v193, v216, v204
	s_setprio 1
	s_waitcnt lgkmcnt(3)
	v_mfma_f32_32x32x16_bf16 v[50:65], v[82:85], v[66:69], v[50:65]
	s_waitcnt lgkmcnt(2)
	v_mfma_f32_32x32x16_bf16 v[34:49], v[86:89], v[66:69], v[34:49]
	s_waitcnt lgkmcnt(1)
	v_mfma_f32_32x32x16_bf16 v[18:33], v[90:93], v[66:69], v[18:33]
	s_waitcnt lgkmcnt(0)
	v_mfma_f32_32x32x16_bf16 v[2:17], v[94:97], v[66:69], v[2:17]
	s_setprio 0
	ds_read_b128 v[66:69], v174 offset:17440
	ds_read_b128 v[82:85], v174 offset:22048
	ds_read_b128 v[86:89], v174 offset:26656
	ds_read_b128 v[90:93], v174 offset:31264
	s_setprio 1
	s_waitcnt lgkmcnt(3)
	v_mfma_f32_32x32x16_bf16 v[50:65], v[66:69], v[70:73], v[50:65]
	s_waitcnt lgkmcnt(2)
	v_mfma_f32_32x32x16_bf16 v[34:49], v[82:85], v[70:73], v[34:49]
	s_waitcnt lgkmcnt(1)
	v_mfma_f32_32x32x16_bf16 v[18:33], v[86:89], v[70:73], v[18:33]
	s_waitcnt lgkmcnt(0)
	v_mfma_f32_32x32x16_bf16 v[2:17], v[90:93], v[70:73], v[2:17]
	s_setprio 0
	ds_read_b128 v[66:69], v174 offset:17472
	ds_read_b128 v[70:73], v174 offset:22080
	ds_read_b128 v[82:85], v174 offset:26688
	ds_read_b128 v[86:89], v174 offset:31296
	s_setprio 1
	s_waitcnt lgkmcnt(3)
	v_mfma_f32_32x32x16_bf16 v[50:65], v[66:69], v[74:77], v[50:65]
	s_waitcnt lgkmcnt(2)
	v_mfma_f32_32x32x16_bf16 v[34:49], v[70:73], v[74:77], v[34:49]
	s_waitcnt lgkmcnt(1)
	v_mfma_f32_32x32x16_bf16 v[18:33], v[82:85], v[74:77], v[18:33]
	s_waitcnt lgkmcnt(0)
	v_mfma_f32_32x32x16_bf16 v[2:17], v[86:89], v[74:77], v[2:17]
	s_setprio 0
	ds_read_b128 v[66:69], v174 offset:17504
	ds_read_b128 v[70:73], v174 offset:22112
	ds_read_b128 v[74:77], v174 offset:26720
	ds_read_b128 v[82:85], v174 offset:31328
	s_setprio 1
	s_waitcnt lgkmcnt(3)
	v_mfma_f32_32x32x16_bf16 v[50:65], v[66:69], v[78:81], v[50:65]
	s_waitcnt lgkmcnt(2)
	v_mfma_f32_32x32x16_bf16 v[34:49], v[70:73], v[78:81], v[34:49]
	s_waitcnt lgkmcnt(1)
	v_mfma_f32_32x32x16_bf16 v[18:33], v[74:77], v[78:81], v[18:33]
	s_waitcnt lgkmcnt(0)
	v_mfma_f32_32x32x16_bf16 v[2:17], v[82:85], v[78:81], v[2:17]
	s_setprio 0
	v_bfe_i32 v83, v218, 0, 1
	v_bfe_i32 v174, v205, 0, 1
	v_bfe_i32 v67, v218, 1, 1
	v_bfe_i32 v175, v205, 1, 1
	v_bfe_i32 v68, v218, 2, 1
	v_bfe_i32 v84, v205, 2, 1
	v_bfe_i32 v69, v218, 3, 1
	v_bfe_i32 v85, v205, 3, 1
	v_bfe_i32 v70, v218, 8, 1
	v_bfe_i32 v86, v205, 8, 1
	v_bfe_i32 v71, v218, 9, 1
	v_bfe_i32 v87, v205, 9, 1
	v_bfe_i32 v72, v218, 10, 1
	v_bfe_i32 v88, v205, 10, 1
	v_bfe_i32 v73, v218, 11, 1
	v_bfe_i32 v89, v205, 11, 1
	v_bfe_i32 v74, v218, 16, 1
	v_bfe_i32 v90, v205, 16, 1
	v_bfe_i32 v75, v218, 17, 1
	v_bfe_i32 v91, v205, 17, 1
	v_bfe_i32 v76, v218, 18, 1
	v_bfe_i32 v92, v205, 18, 1
	v_bfe_i32 v77, v218, 19, 1
	v_bfe_i32 v93, v205, 19, 1
	v_bfe_i32 v78, v218, 24, 1
	v_bfe_i32 v94, v205, 24, 1
	v_bfe_i32 v79, v218, 25, 1
	v_bfe_i32 v95, v205, 25, 1
	v_bfe_i32 v80, v218, 26, 1
	v_bfe_i32 v96, v205, 26, 1
	v_bfe_i32 v66, v218, 27, 1
	v_bfe_i32 v82, v205, 27, 1
	s_nop 0
	v_bfi_b32 v79, v79, v230, v231
	v_bfi_b32 v81, v66, v230, v231
	v_bfi_b32 v66, v83, v230, v231
	v_bfi_b32 v97, v82, v230, v231
	v_bfi_b32 v83, v175, v230, v231
	v_bfi_b32 v82, v174, v230, v231
	ds_read_b128 v[174:177], v217 offset:8704
	ds_read_b128 v[218:221], v217
	ds_read_b128 v[222:225], v217 offset:32
	ds_read_b128 v[226:229], v217 offset:8736
	ds_read_b128 v[232:235], v217 offset:64
	ds_read_b128 v[236:239], v217 offset:8768
	ds_read_b128 v[240:243], v217 offset:96
	ds_read_b128 v[248:251], v217 offset:8800
	v_bfi_b32 v80, v80, v230, v231
	v_bfi_b32 v78, v78, v230, v231
	v_bfi_b32 v77, v77, v230, v231
	v_bfi_b32 v76, v76, v230, v231
	v_bfi_b32 v75, v75, v230, v231
	v_bfi_b32 v74, v74, v230, v231
	v_bfi_b32 v73, v73, v230, v231
	v_bfi_b32 v72, v72, v230, v231
	v_bfi_b32 v71, v71, v230, v231
	v_bfi_b32 v70, v70, v230, v231
	v_bfi_b32 v69, v69, v230, v231
	v_bfi_b32 v68, v68, v230, v231
	v_bfi_b32 v67, v67, v230, v231
	v_bfi_b32 v96, v96, v230, v231
	v_bfi_b32 v95, v95, v230, v231
	v_bfi_b32 v94, v94, v230, v231
	v_bfi_b32 v93, v93, v230, v231
	v_bfi_b32 v92, v92, v230, v231
	v_bfi_b32 v91, v91, v230, v231
	v_bfi_b32 v90, v90, v230, v231
	v_bfi_b32 v89, v89, v230, v231
	v_bfi_b32 v88, v88, v230, v231
	v_bfi_b32 v87, v87, v230, v231
	v_bfi_b32 v86, v86, v230, v231
	v_bfi_b32 v85, v85, v230, v231
	v_bfi_b32 v84, v84, v230, v231
	s_setprio 1
	s_waitcnt lgkmcnt(6)
	v_mfma_f32_32x32x16_bf16 v[66:81], v[218:221], v[98:101], v[66:81]
	v_mfma_f32_32x32x16_bf16 v[82:97], v[174:177], v[98:101], v[82:97]
	s_waitcnt lgkmcnt(5)
	v_mfma_f32_32x32x16_bf16 v[66:81], v[222:225], v[102:105], v[66:81]
	s_waitcnt lgkmcnt(4)
	v_mfma_f32_32x32x16_bf16 v[82:97], v[226:229], v[102:105], v[82:97]
	s_waitcnt lgkmcnt(3)
	v_mfma_f32_32x32x16_bf16 v[66:81], v[232:235], v[106:109], v[66:81]
	s_waitcnt lgkmcnt(2)
	v_mfma_f32_32x32x16_bf16 v[82:97], v[236:239], v[106:109], v[82:97]
	s_waitcnt lgkmcnt(1)
	v_mfma_f32_32x32x16_bf16 v[66:81], v[240:243], v[110:113], v[66:81]
	s_waitcnt lgkmcnt(0)
	v_mfma_f32_32x32x16_bf16 v[82:97], v[248:251], v[110:113], v[82:97]
	s_setprio 0
	ds_read_b128 v[174:177], v217 offset:128
	ds_read_b128 v[218:221], v217 offset:160
	ds_read_b128 v[222:225], v217 offset:8832
	ds_read_b128 v[226:229], v217 offset:8864
	ds_read_b128 v[232:235], v217 offset:192
	ds_read_b128 v[236:239], v217 offset:224
	ds_read_b128 v[240:243], v217 offset:8896
	ds_read_b128 v[248:251], v217 offset:8928
	s_setprio 1
	s_waitcnt lgkmcnt(7)
	v_mfma_f32_32x32x16_bf16 v[66:81], v[174:177], v[114:117], v[66:81]
	s_waitcnt lgkmcnt(5)
	v_mfma_f32_32x32x16_bf16 v[82:97], v[222:225], v[114:117], v[82:97]
	v_mfma_f32_32x32x16_bf16 v[66:81], v[218:221], v[118:121], v[66:81]
	s_waitcnt lgkmcnt(4)
	v_mfma_f32_32x32x16_bf16 v[82:97], v[226:229], v[118:121], v[82:97]
	s_waitcnt lgkmcnt(3)
	v_mfma_f32_32x32x16_bf16 v[66:81], v[232:235], v[122:125], v[66:81]
	s_waitcnt lgkmcnt(1)
	v_mfma_f32_32x32x16_bf16 v[82:97], v[240:243], v[122:125], v[82:97]
	v_mfma_f32_32x32x16_bf16 v[66:81], v[236:239], v[126:129], v[66:81]
	s_waitcnt lgkmcnt(0)
	v_mfma_f32_32x32x16_bf16 v[82:97], v[248:251], v[126:129], v[82:97]
	s_setprio 0
	s_or_b64 exec, exec, s[0:1]
	s_and_b64 vcc, exec, s[8:9]
	s_cbranch_vccz .LBB0_88
	s_branch .LBB0_89
